# M3 mix_out: one static s_setprio 1 for the retention waves (0-3) that carry the rotary work (on top of the M1 attention raise)
# speedup vs baseline: 1.0136x; 1.0042x over previous
.LBB0_876:
	v_add_f32_e32 v32, 0x358637bd, v35
	v_cmp_gt_f32_e32 vcc, s73, v32
	v_mul_f32_e32 v33, 0x4f800000, v32
	v_ashrrev_i32_e32 v113, 31, v112
	v_cndmask_b32_e32 v32, v32, v33, vcc
	v_sqrt_f32_e32 v33, v32
	s_add_i32 s2, s2, s72
	s_cmpk_gt_i32 s2, 0xff
	s_waitcnt lgkmcnt(0)
	v_add_u32_e32 v34, -1, v33
	v_fma_f32 v35, -v34, v33, v32
	v_cmp_ge_f32_e64 s[38:39], 0, v35
	v_add_u32_e32 v35, 1, v33
	s_nop 0
	v_cndmask_b32_e64 v34, v33, v34, s[38:39]
	v_fma_f32 v33, -v35, v33, v32
	v_cmp_lt_f32_e64 s[38:39], 0, v33
	s_nop 1
	v_cndmask_b32_e64 v33, v34, v35, s[38:39]
	v_mul_f32_e32 v34, 0x37800000, v33
	v_cndmask_b32_e32 v33, v33, v34, vcc
	v_cmp_class_f32_e32 vcc, v32, v236
	s_nop 1
	v_cndmask_b32_e32 v32, v33, v32, vcc
	v_div_scale_f32 v33, s[4:5], v32, v32, 1.0
	v_rcp_f32_e32 v34, v33
	s_nop 0
	v_fma_f32 v35, -v33, v34, 1.0
	v_fmac_f32_e32 v34, v35, v34
	v_div_scale_f32 v35, vcc, 1.0, v32, 1.0
	v_mul_f32_e32 v37, v35, v34
	v_fma_f32 v38, -v33, v37, v35
	v_fmac_f32_e32 v37, v38, v34
	v_fma_f32 v33, -v33, v37, v35
	v_div_fmas_f32 v33, v33, v34, v37
	v_div_fixup_f32 v38, v33, v32, 1.0
	v_mov_b64_e32 v[32:33], s[34:35]
	v_mad_i64_i32 v[32:33], s[4:5], v112, s84, v[32:33]
	v_lshlrev_b64 v[34:35], 11, v[112:113]
	v_lshl_add_u64 v[32:33], v[192:193], 1, v[32:33]
	v_lshl_add_u64 v[34:35], s[20:21], 0, v[34:35]
	v_lshl_add_u64 v[34:35], s[42:43], 1, v[34:35]
	v_lshl_add_u64 v[40:41], v[32:33], 0, v[70:71]
	v_lshl_add_u64 v[42:43], s[26:27], 1, v[34:35]
	global_load_dwordx2 v[44:45], v[40:41], off
	global_load_dwordx4 v[32:35], v[68:69], off
	global_load_dwordx2 v[156:157], v[40:41], off offset:16
	global_load_dwordx2 v[158:159], v[40:41], off offset:32
	global_load_dwordx2 v[160:161], v[40:41], off offset:48
	global_load_dwordx2 v[162:163], v[40:41], off offset:64
	global_load_dwordx2 v[164:165], v[40:41], off offset:80
	global_load_dwordx2 v[166:167], v[40:41], off offset:96
	global_load_dwordx2 v[168:169], v[40:41], off offset:112
	global_load_dwordx4 v[172:175], v[68:69], off offset:32
	global_load_dwordx4 v[176:179], v[68:69], off offset:64
	global_load_dwordx4 v[180:183], v[68:69], off offset:96
	global_load_dwordx4 v[184:187], v[68:69], off offset:128
	global_load_dwordx4 v[188:191], v[68:69], off offset:160
	global_load_dwordx4 v[206:209], v[68:69], off offset:192
	global_load_dwordx4 v[210:213], v[68:69], off offset:224
	v_pk_add_f32 v[16:17], v[16:17], v[36:37] op_sel_hi:[1,0] neg_lo:[0,1] neg_hi:[0,1]
	s_waitcnt vmcnt(15)
	v_and_b32_e32 v39, 0xffff0000, v44
	v_lshlrev_b32_e32 v37, 16, v44
	v_pk_mul_f32 v[16:17], v[16:17], v[38:39] op_sel_hi:[1,0]
	v_mul_f32_e32 v44, 0xbfb8aa3b, v37
	s_waitcnt vmcnt(14)
	v_pk_mul_f32 v[16:17], v[32:33], v[16:17]
	v_mul_f32_e32 v32, 0xbfb8aa3b, v39
	v_exp_f32_e32 v46, v44
	v_exp_f32_e32 v47, v32
	v_pk_add_f32 v[18:19], v[18:19], v[36:37] op_sel_hi:[1,0] neg_lo:[0,1] neg_hi:[0,1]
	v_pk_add_f32 v[32:33], v[46:47], 1.0 op_sel_hi:[1,0]
	s_nop 0
	v_div_scale_f32 v44, s[4:5], v33, v33, v39
	v_rcp_f32_e32 v46, v44
	s_nop 0
	v_fma_f32 v47, -v44, v46, 1.0
	v_fmac_f32_e32 v46, v47, v46
	v_div_scale_f32 v47, vcc, v39, v33, v39
	v_mul_f32_e32 v48, v47, v46
	v_fma_f32 v49, -v44, v48, v47
	v_fmac_f32_e32 v48, v49, v46
	v_fma_f32 v44, -v44, v48, v47
	v_div_fmas_f32 v44, v44, v46, v48
	v_div_fixup_f32 v33, v44, v33, v39
	v_div_scale_f32 v39, s[4:5], v32, v32, v37
	v_rcp_f32_e32 v44, v39
	s_nop 0
	v_fma_f32 v46, -v39, v44, 1.0
	v_fmac_f32_e32 v44, v46, v44
	v_div_scale_f32 v46, vcc, v37, v32, v37
	v_mul_f32_e32 v47, v46, v44
	v_fma_f32 v48, -v39, v47, v46
	v_fmac_f32_e32 v47, v48, v44
	v_fma_f32 v39, -v39, v47, v46
	v_div_fmas_f32 v39, v39, v44, v47
	v_div_fixup_f32 v32, v39, v32, v37
	v_lshlrev_b32_e32 v37, 16, v45
	v_and_b32_e32 v39, 0xffff0000, v45
	v_pk_mul_f32 v[16:17], v[16:17], v[32:33]
	v_mul_f32_e32 v32, 0xbfb8aa3b, v37
	v_mul_f32_e32 v33, 0xbfb8aa3b, v39
	v_exp_f32_e32 v32, v32
	v_exp_f32_e32 v33, v33
	v_pk_mul_f32 v[18:19], v[18:19], v[38:39] op_sel_hi:[1,0]
	v_pk_add_f32 v[32:33], v[32:33], 1.0 op_sel_hi:[1,0]
	v_pk_mul_f32 v[18:19], v[34:35], v[18:19]
	v_div_scale_f32 v34, s[4:5], v33, v33, v39
	v_rcp_f32_e32 v35, v34
	s_nop 0
	v_fma_f32 v44, -v34, v35, 1.0
	v_fmac_f32_e32 v35, v44, v35
	v_div_scale_f32 v44, vcc, v39, v33, v39
	v_mul_f32_e32 v45, v44, v35
	v_fma_f32 v46, -v34, v45, v44
	v_fmac_f32_e32 v45, v46, v35
	v_fma_f32 v34, -v34, v45, v44
	v_div_fmas_f32 v34, v34, v35, v45
	v_div_fixup_f32 v33, v34, v33, v39
	v_div_scale_f32 v34, s[4:5], v32, v32, v37
	v_rcp_f32_e32 v35, v34
	s_nop 0
	v_fma_f32 v39, -v34, v35, 1.0
	v_fmac_f32_e32 v35, v39, v35
	v_div_scale_f32 v39, vcc, v37, v32, v37
	v_mul_f32_e32 v44, v39, v35
	v_fma_f32 v45, -v34, v44, v39
	v_fmac_f32_e32 v44, v45, v35
	v_fma_f32 v34, -v34, v44, v39
	v_div_fmas_f32 v34, v34, v35, v44
	v_div_fixup_f32 v32, v34, v32, v37
	v_pk_mul_f32 v[18:19], v[18:19], v[32:33]
	v_cvt_pk_bf16_f32 v32, v16, v17
	v_cvt_pk_bf16_f32 v33, v18, v19
	v_lshl_add_u64 v[16:17], v[42:43], 0, v[70:71]
	global_store_dwordx2 v[16:17], v[32:33], off
	s_waitcnt vmcnt(1)
	v_mov_b64_e32 v[42:43], v[156:157]
	v_mov_b64_e32 v[32:33], v[172:173]
	v_mov_b64_e32 v[34:35], v[174:175]
	v_pk_add_f32 v[18:19], v[20:21], v[36:37] op_sel_hi:[1,0] neg_lo:[0,1] neg_hi:[0,1]
	v_lshlrev_b32_e32 v37, 16, v42
	v_and_b32_e32 v39, 0xffff0000, v42
	v_mul_f32_e32 v20, 0xbfb8aa3b, v37
	v_mul_f32_e32 v21, 0xbfb8aa3b, v39
	v_exp_f32_e32 v20, v20
	v_exp_f32_e32 v21, v21
	v_pk_mul_f32 v[18:19], v[18:19], v[38:39] op_sel_hi:[1,0]
	v_pk_add_f32 v[20:21], v[20:21], 1.0 op_sel_hi:[1,0]
	v_pk_mul_f32 v[18:19], v[18:19], v[32:33]
	v_div_scale_f32 v32, s[4:5], v21, v21, v39
	v_rcp_f32_e32 v33, v32
	s_nop 0
	v_fma_f32 v42, -v32, v33, 1.0
	v_fmac_f32_e32 v33, v42, v33
	v_div_scale_f32 v42, vcc, v39, v21, v39
	v_mul_f32_e32 v44, v42, v33
	v_fma_f32 v45, -v32, v44, v42
	v_fmac_f32_e32 v44, v45, v33
	v_fma_f32 v32, -v32, v44, v42
	v_div_fmas_f32 v32, v32, v33, v44
	v_div_fixup_f32 v21, v32, v21, v39
	v_div_scale_f32 v32, s[4:5], v20, v20, v37
	v_rcp_f32_e32 v33, v32
	s_nop 0
	v_fma_f32 v39, -v32, v33, 1.0
	v_fmac_f32_e32 v33, v39, v33
	v_div_scale_f32 v39, vcc, v37, v20, v37
	v_mul_f32_e32 v42, v39, v33
	v_fma_f32 v44, -v32, v42, v39
	v_fmac_f32_e32 v42, v44, v33
	v_fma_f32 v32, -v32, v42, v39
	v_div_fmas_f32 v32, v32, v33, v42
	v_div_fixup_f32 v20, v32, v20, v37
	v_lshlrev_b32_e32 v32, 16, v43
	v_and_b32_e32 v33, 0xffff0000, v43
	v_pk_mul_f32 v[18:19], v[18:19], v[20:21]
	v_pk_add_f32 v[20:21], v[22:23], v[36:37] op_sel_hi:[1,0] neg_lo:[0,1] neg_hi:[0,1]
	v_mul_f32_e32 v22, 0xbfb8aa3b, v32
	v_mul_f32_e32 v23, 0xbfb8aa3b, v33
	v_exp_f32_e32 v22, v22
	v_exp_f32_e32 v23, v23
	v_pk_mul_f32 v[20:21], v[20:21], v[38:39] op_sel_hi:[1,0]
	v_cvt_pk_bf16_f32 v18, v18, v19
	v_pk_mul_f32 v[20:21], v[20:21], v[34:35]
	v_pk_add_f32 v[22:23], v[22:23], 1.0 op_sel_hi:[1,0]
	s_nop 0
	v_div_scale_f32 v34, s[4:5], v23, v23, v33
	v_rcp_f32_e32 v35, v34
	s_nop 0
	v_fma_f32 v37, -v34, v35, 1.0
	v_fmac_f32_e32 v35, v37, v35
	v_div_scale_f32 v37, vcc, v33, v23, v33
	v_mul_f32_e32 v39, v37, v35
	v_fma_f32 v42, -v34, v39, v37
	v_fmac_f32_e32 v39, v42, v35
	v_fma_f32 v34, -v34, v39, v37
	v_div_fmas_f32 v34, v34, v35, v39
	v_div_fixup_f32 v23, v34, v23, v33
	v_div_scale_f32 v33, s[4:5], v22, v22, v32
	v_rcp_f32_e32 v34, v33
	s_nop 0
	v_fma_f32 v35, -v33, v34, 1.0
	v_fmac_f32_e32 v34, v35, v34
	v_div_scale_f32 v35, vcc, v32, v22, v32
	v_mul_f32_e32 v37, v35, v34
	v_fma_f32 v39, -v33, v37, v35
	v_fmac_f32_e32 v37, v39, v34
	v_fma_f32 v33, -v33, v37, v35
	v_div_fmas_f32 v33, v33, v34, v37
	v_div_fixup_f32 v22, v33, v22, v32
	v_pk_mul_f32 v[20:21], v[20:21], v[22:23]
	v_pk_add_f32 v[24:25], v[24:25], v[36:37] op_sel_hi:[1,0] neg_lo:[0,1] neg_hi:[0,1]
	v_cvt_pk_bf16_f32 v19, v20, v21
	global_store_dwordx2 v[16:17], v[18:19], off offset:16
	s_waitcnt vmcnt(2)
	v_mov_b64_e32 v[22:23], v[158:159]
	v_mov_b64_e32 v[18:19], v[176:177]
	v_mov_b64_e32 v[20:21], v[178:179]
	v_pk_mul_f32 v[24:25], v[24:25], v[38:39] op_sel_hi:[1,0]
	v_lshlrev_b32_e32 v34, 16, v22
	v_and_b32_e32 v22, 0xffff0000, v22
	v_mul_f32_e32 v32, 0xbfb8aa3b, v34
	v_pk_mul_f32 v[18:19], v[24:25], v[18:19]
	v_mul_f32_e32 v24, 0xbfb8aa3b, v22
	v_exp_f32_e32 v32, v32
	v_exp_f32_e32 v33, v24
	s_nop 0
	v_pk_add_f32 v[24:25], v[32:33], 1.0 op_sel_hi:[1,0]
	s_nop 0
	v_div_scale_f32 v32, s[4:5], v25, v25, v22
	v_rcp_f32_e32 v33, v32
	s_nop 0
	v_fma_f32 v35, -v32, v33, 1.0
	v_fmac_f32_e32 v33, v35, v33
	v_div_scale_f32 v35, vcc, v22, v25, v22
	v_mul_f32_e32 v37, v35, v33
	v_fma_f32 v39, -v32, v37, v35
	v_fmac_f32_e32 v37, v39, v33
	v_fma_f32 v32, -v32, v37, v35
	v_div_fmas_f32 v32, v32, v33, v37
	v_div_fixup_f32 v25, v32, v25, v22
	v_div_scale_f32 v22, s[4:5], v24, v24, v34
	v_rcp_f32_e32 v32, v22
	s_nop 0
	v_fma_f32 v33, -v22, v32, 1.0
	v_fmac_f32_e32 v32, v33, v32
	v_div_scale_f32 v33, vcc, v34, v24, v34
	v_mul_f32_e32 v35, v33, v32
	v_fma_f32 v37, -v22, v35, v33
	v_fmac_f32_e32 v35, v37, v32
	v_fma_f32 v22, -v22, v35, v33
	v_div_fmas_f32 v22, v22, v32, v35
	v_div_fixup_f32 v24, v22, v24, v34
	v_pk_mul_f32 v[18:19], v[18:19], v[24:25]
	v_pk_add_f32 v[24:25], v[26:27], v[36:37] op_sel_hi:[1,0] neg_lo:[0,1] neg_hi:[0,1]
	v_lshlrev_b32_e32 v26, 16, v23
	v_and_b32_e32 v27, 0xffff0000, v23
	v_mul_f32_e32 v22, 0xbfb8aa3b, v26
	v_mul_f32_e32 v23, 0xbfb8aa3b, v27
	v_exp_f32_e32 v22, v22
	v_exp_f32_e32 v23, v23
	v_pk_mul_f32 v[24:25], v[24:25], v[38:39] op_sel_hi:[1,0]
	v_cvt_pk_bf16_f32 v18, v18, v19
	v_pk_mul_f32 v[20:21], v[24:25], v[20:21]
	v_pk_add_f32 v[22:23], v[22:23], 1.0 op_sel_hi:[1,0]
	v_pk_add_f32 v[0:1], v[0:1], v[36:37] op_sel_hi:[1,0] neg_lo:[0,1] neg_hi:[0,1]
	v_div_scale_f32 v24, s[4:5], v23, v23, v27
	v_rcp_f32_e32 v25, v24
	v_pk_mul_f32 v[0:1], v[0:1], v[38:39] op_sel_hi:[1,0]
	v_pk_add_f32 v[2:3], v[2:3], v[36:37] op_sel_hi:[1,0] neg_lo:[0,1] neg_hi:[0,1]
	v_pk_add_f32 v[4:5], v[4:5], v[36:37] op_sel_hi:[1,0] neg_lo:[0,1] neg_hi:[0,1]
	v_fma_f32 v32, -v24, v25, 1.0
	v_fmac_f32_e32 v25, v32, v25
	v_div_scale_f32 v32, vcc, v27, v23, v27
	v_mul_f32_e32 v33, v32, v25
	v_fma_f32 v34, -v24, v33, v32
	v_fmac_f32_e32 v33, v34, v25
	v_fma_f32 v24, -v24, v33, v32
	v_div_fmas_f32 v24, v24, v25, v33
	v_div_fixup_f32 v23, v24, v23, v27
	v_div_scale_f32 v24, s[4:5], v22, v22, v26
	v_rcp_f32_e32 v25, v24
	v_pk_mul_f32 v[2:3], v[2:3], v[38:39] op_sel_hi:[1,0]
	v_pk_mul_f32 v[4:5], v[4:5], v[38:39] op_sel_hi:[1,0]
	v_fma_f32 v27, -v24, v25, 1.0
	v_fmac_f32_e32 v25, v27, v25
	v_div_scale_f32 v27, vcc, v26, v22, v26
	v_mul_f32_e32 v32, v27, v25
	v_fma_f32 v33, -v24, v32, v27
	v_fmac_f32_e32 v32, v33, v25
	v_fma_f32 v24, -v24, v32, v27
	v_div_fmas_f32 v24, v24, v25, v32
	v_div_fixup_f32 v22, v24, v22, v26
	v_pk_mul_f32 v[20:21], v[20:21], v[22:23]
	v_pk_add_f32 v[24:25], v[28:29], v[36:37] op_sel_hi:[1,0] neg_lo:[0,1] neg_hi:[0,1]
	v_cvt_pk_bf16_f32 v19, v20, v21
	global_store_dwordx2 v[16:17], v[18:19], off offset:32
	s_waitcnt vmcnt(3)
	v_mov_b64_e32 v[22:23], v[160:161]
	v_mov_b64_e32 v[18:19], v[180:181]
	v_mov_b64_e32 v[20:21], v[182:183]
	v_pk_mul_f32 v[24:25], v[24:25], v[38:39] op_sel_hi:[1,0]
	v_lshlrev_b32_e32 v28, 16, v22
	v_and_b32_e32 v22, 0xffff0000, v22
	v_mul_f32_e32 v26, 0xbfb8aa3b, v28
	v_pk_mul_f32 v[18:19], v[24:25], v[18:19]
	v_mul_f32_e32 v24, 0xbfb8aa3b, v22
	v_exp_f32_e32 v26, v26
	v_exp_f32_e32 v27, v24
	s_nop 0
	v_pk_add_f32 v[24:25], v[26:27], 1.0 op_sel_hi:[1,0]
	s_nop 0
	v_div_scale_f32 v26, s[4:5], v25, v25, v22
	v_rcp_f32_e32 v27, v26
	s_nop 0
	v_fma_f32 v29, -v26, v27, 1.0
	v_fmac_f32_e32 v27, v29, v27
	v_div_scale_f32 v29, vcc, v22, v25, v22
	v_mul_f32_e32 v32, v29, v27
	v_fma_f32 v33, -v26, v32, v29
	v_fmac_f32_e32 v32, v33, v27
	v_fma_f32 v26, -v26, v32, v29
	v_div_fmas_f32 v26, v26, v27, v32
	v_div_fixup_f32 v25, v26, v25, v22
	v_div_scale_f32 v22, s[4:5], v24, v24, v28
	v_rcp_f32_e32 v26, v22
	s_nop 0
	v_fma_f32 v27, -v22, v26, 1.0
	v_fmac_f32_e32 v26, v27, v26
	v_div_scale_f32 v27, vcc, v28, v24, v28
	v_mul_f32_e32 v29, v27, v26
	v_fma_f32 v32, -v22, v29, v27
	v_fmac_f32_e32 v29, v32, v26
	v_fma_f32 v22, -v22, v29, v27
	v_div_fmas_f32 v22, v22, v26, v29
	v_lshlrev_b32_e32 v26, 16, v23
	v_and_b32_e32 v27, 0xffff0000, v23
	v_div_fixup_f32 v24, v22, v24, v28
	v_mul_f32_e32 v22, 0xbfb8aa3b, v26
	v_mul_f32_e32 v23, 0xbfb8aa3b, v27
	v_exp_f32_e32 v22, v22
	v_exp_f32_e32 v23, v23
	v_pk_mul_f32 v[18:19], v[18:19], v[24:25]
	v_pk_add_f32 v[24:25], v[30:31], v[36:37] op_sel_hi:[1,0] neg_lo:[0,1] neg_hi:[0,1]
	v_cvt_pk_bf16_f32 v18, v18, v19
	v_pk_mul_f32 v[24:25], v[24:25], v[38:39] op_sel_hi:[1,0]
	v_pk_add_f32 v[22:23], v[22:23], 1.0 op_sel_hi:[1,0]
	v_pk_mul_f32 v[20:21], v[24:25], v[20:21]
	v_div_scale_f32 v24, s[4:5], v23, v23, v27
	v_rcp_f32_e32 v25, v24
	s_nop 0
	v_fma_f32 v28, -v24, v25, 1.0
	v_fmac_f32_e32 v25, v28, v25
	v_div_scale_f32 v28, vcc, v27, v23, v27
	v_mul_f32_e32 v29, v28, v25
	v_fma_f32 v30, -v24, v29, v28
	v_fmac_f32_e32 v29, v30, v25
	v_fma_f32 v24, -v24, v29, v28
	v_div_fmas_f32 v24, v24, v25, v29
	v_div_fixup_f32 v23, v24, v23, v27
	v_div_scale_f32 v24, s[4:5], v22, v22, v26
	v_rcp_f32_e32 v25, v24
	s_nop 0
	v_fma_f32 v27, -v24, v25, 1.0
	v_fmac_f32_e32 v25, v27, v25
	v_div_scale_f32 v27, vcc, v26, v22, v26
	v_mul_f32_e32 v28, v27, v25
	v_fma_f32 v29, -v24, v28, v27
	v_fmac_f32_e32 v28, v29, v25
	v_fma_f32 v24, -v24, v28, v27
	v_div_fmas_f32 v24, v24, v25, v28
	v_div_fixup_f32 v22, v24, v22, v26
	v_pk_mul_f32 v[20:21], v[20:21], v[22:23]
	s_nop 0
	v_cvt_pk_bf16_f32 v19, v20, v21
	global_store_dwordx2 v[16:17], v[18:19], off offset:48
	s_waitcnt vmcnt(4)
	v_mov_b64_e32 v[22:23], v[162:163]
	v_mov_b64_e32 v[18:19], v[184:185]
	v_mov_b64_e32 v[20:21], v[186:187]
	v_lshlrev_b32_e32 v26, 16, v22
	v_and_b32_e32 v22, 0xffff0000, v22
	v_mul_f32_e32 v24, 0xbfb8aa3b, v26
	v_pk_mul_f32 v[0:1], v[0:1], v[18:19]
	v_mul_f32_e32 v18, 0xbfb8aa3b, v22
	v_exp_f32_e32 v24, v24
	v_exp_f32_e32 v25, v18
	v_pk_mul_f32 v[2:3], v[2:3], v[20:21]
	v_pk_add_f32 v[18:19], v[24:25], 1.0 op_sel_hi:[1,0]
	s_nop 0
	v_div_scale_f32 v24, s[4:5], v19, v19, v22
	v_rcp_f32_e32 v25, v24
	s_nop 0
	v_fma_f32 v27, -v24, v25, 1.0
	v_fmac_f32_e32 v25, v27, v25
	v_div_scale_f32 v27, vcc, v22, v19, v22
	v_mul_f32_e32 v28, v27, v25
	v_fma_f32 v29, -v24, v28, v27
	v_fmac_f32_e32 v28, v29, v25
	v_fma_f32 v24, -v24, v28, v27
	v_div_fmas_f32 v24, v24, v25, v28
	v_div_fixup_f32 v19, v24, v19, v22
	v_div_scale_f32 v22, s[4:5], v18, v18, v26
	v_rcp_f32_e32 v24, v22
	s_nop 0
	v_fma_f32 v25, -v22, v24, 1.0
	v_fmac_f32_e32 v24, v25, v24
	v_div_scale_f32 v25, vcc, v26, v18, v26
	v_mul_f32_e32 v27, v25, v24
	v_fma_f32 v28, -v22, v27, v25
	v_fmac_f32_e32 v27, v28, v24
	v_fma_f32 v22, -v22, v27, v25
	v_div_fmas_f32 v22, v22, v24, v27
	v_div_fixup_f32 v18, v22, v18, v26
	v_lshlrev_b32_e32 v22, 16, v23
	v_and_b32_e32 v23, 0xffff0000, v23
	v_pk_mul_f32 v[0:1], v[0:1], v[18:19]
	v_mul_f32_e32 v18, 0xbfb8aa3b, v22
	v_mul_f32_e32 v19, 0xbfb8aa3b, v23
	v_exp_f32_e32 v18, v18
	v_exp_f32_e32 v19, v19
	v_cvt_pk_bf16_f32 v0, v0, v1
	v_pk_add_f32 v[18:19], v[18:19], 1.0 op_sel_hi:[1,0]
	s_nop 0
	v_div_scale_f32 v20, s[4:5], v19, v19, v23
	v_rcp_f32_e32 v21, v20
	s_nop 0
	v_fma_f32 v24, -v20, v21, 1.0
	v_fmac_f32_e32 v21, v24, v21
	v_div_scale_f32 v24, vcc, v23, v19, v23
	v_mul_f32_e32 v25, v24, v21
	v_fma_f32 v26, -v20, v25, v24
	v_fmac_f32_e32 v25, v26, v21
	v_fma_f32 v20, -v20, v25, v24
	v_div_fmas_f32 v20, v20, v21, v25
	v_div_fixup_f32 v19, v20, v19, v23
	v_div_scale_f32 v20, s[4:5], v18, v18, v22
	v_rcp_f32_e32 v21, v20
	s_nop 0
	v_fma_f32 v23, -v20, v21, 1.0
	v_fmac_f32_e32 v21, v23, v21
	v_div_scale_f32 v23, vcc, v22, v18, v22
	v_mul_f32_e32 v24, v23, v21
	v_fma_f32 v25, -v20, v24, v23
	v_fmac_f32_e32 v24, v25, v21
	v_fma_f32 v20, -v20, v24, v23
	v_div_fmas_f32 v20, v20, v21, v24
	v_div_fixup_f32 v18, v20, v18, v22
	v_pk_mul_f32 v[2:3], v[2:3], v[18:19]
	s_nop 0
	v_cvt_pk_bf16_f32 v1, v2, v3
	global_store_dwordx2 v[16:17], v[0:1], off offset:64
	s_waitcnt vmcnt(5)
	v_mov_b64_e32 v[18:19], v[164:165]
	v_mov_b64_e32 v[0:1], v[188:189]
	v_mov_b64_e32 v[2:3], v[190:191]
	v_lshlrev_b32_e32 v22, 16, v18
	v_and_b32_e32 v18, 0xffff0000, v18
	v_mul_f32_e32 v20, 0xbfb8aa3b, v22
	v_pk_mul_f32 v[0:1], v[4:5], v[0:1]
	v_mul_f32_e32 v4, 0xbfb8aa3b, v18
	v_exp_f32_e32 v20, v20
	v_exp_f32_e32 v21, v4
	s_nop 0
	v_pk_add_f32 v[4:5], v[20:21], 1.0 op_sel_hi:[1,0]
	s_nop 0
	v_div_scale_f32 v20, s[4:5], v5, v5, v18
	v_rcp_f32_e32 v21, v20
	s_nop 0
	v_fma_f32 v23, -v20, v21, 1.0
	v_fmac_f32_e32 v21, v23, v21
	v_div_scale_f32 v23, vcc, v18, v5, v18
	v_mul_f32_e32 v24, v23, v21
	v_fma_f32 v25, -v20, v24, v23
	v_fmac_f32_e32 v24, v25, v21
	v_fma_f32 v20, -v20, v24, v23
	v_div_fmas_f32 v20, v20, v21, v24
	v_div_fixup_f32 v5, v20, v5, v18
	v_div_scale_f32 v18, s[4:5], v4, v4, v22
	v_rcp_f32_e32 v20, v18
	s_nop 0
	v_fma_f32 v21, -v18, v20, 1.0
	v_fmac_f32_e32 v20, v21, v20
	v_div_scale_f32 v21, vcc, v22, v4, v22
	v_mul_f32_e32 v23, v21, v20
	v_fma_f32 v24, -v18, v23, v21
	v_fmac_f32_e32 v23, v24, v20
	v_fma_f32 v18, -v18, v23, v21
	v_div_fmas_f32 v18, v18, v20, v23
	v_div_fixup_f32 v4, v18, v4, v22
	v_pk_mul_f32 v[0:1], v[0:1], v[4:5]
	v_pk_add_f32 v[4:5], v[6:7], v[36:37] op_sel_hi:[1,0] neg_lo:[0,1] neg_hi:[0,1]
	v_lshlrev_b32_e32 v18, 16, v19
	v_and_b32_e32 v19, 0xffff0000, v19
	v_pk_mul_f32 v[4:5], v[4:5], v[38:39] op_sel_hi:[1,0]
	v_mul_f32_e32 v6, 0xbfb8aa3b, v18
	v_pk_mul_f32 v[2:3], v[4:5], v[2:3]
	v_mul_f32_e32 v4, 0xbfb8aa3b, v19
	v_exp_f32_e32 v6, v6
	v_exp_f32_e32 v7, v4
	v_cvt_pk_bf16_f32 v0, v0, v1
	v_pk_add_f32 v[4:5], v[6:7], 1.0 op_sel_hi:[1,0]
	s_nop 0
	v_div_scale_f32 v6, s[4:5], v5, v5, v19
	v_rcp_f32_e32 v7, v6
	s_nop 0
	v_fma_f32 v20, -v6, v7, 1.0
	v_fmac_f32_e32 v7, v20, v7
	v_div_scale_f32 v20, vcc, v19, v5, v19
	v_mul_f32_e32 v21, v20, v7
	v_fma_f32 v22, -v6, v21, v20
	v_fmac_f32_e32 v21, v22, v7
	v_fma_f32 v6, -v6, v21, v20
	v_div_fmas_f32 v6, v6, v7, v21
	v_div_fixup_f32 v5, v6, v5, v19
	v_div_scale_f32 v6, s[4:5], v4, v4, v18
	v_rcp_f32_e32 v7, v6
	s_nop 0
	v_fma_f32 v19, -v6, v7, 1.0
	v_fmac_f32_e32 v7, v19, v7
	v_div_scale_f32 v19, vcc, v18, v4, v18
	v_mul_f32_e32 v20, v19, v7
	v_fma_f32 v21, -v6, v20, v19
	v_fmac_f32_e32 v20, v21, v7
	v_fma_f32 v6, -v6, v20, v19
	v_div_fmas_f32 v6, v6, v7, v20
	v_div_fixup_f32 v4, v6, v4, v18
	v_pk_mul_f32 v[2:3], v[2:3], v[4:5]
	v_pk_add_f32 v[6:7], v[8:9], v[36:37] op_sel_hi:[1,0] neg_lo:[0,1] neg_hi:[0,1]
	v_cvt_pk_bf16_f32 v1, v2, v3
	global_store_dwordx2 v[16:17], v[0:1], off offset:80
	s_waitcnt vmcnt(6)
	v_mov_b64_e32 v[4:5], v[166:167]
	v_mov_b64_e32 v[0:1], v[206:207]
	v_mov_b64_e32 v[2:3], v[208:209]
	v_pk_mul_f32 v[6:7], v[6:7], v[38:39] op_sel_hi:[1,0]
	v_lshlrev_b32_e32 v18, 16, v4
	v_and_b32_e32 v4, 0xffff0000, v4
	v_mul_f32_e32 v8, 0xbfb8aa3b, v18
	v_pk_mul_f32 v[0:1], v[6:7], v[0:1]
	v_mul_f32_e32 v6, 0xbfb8aa3b, v4
	v_exp_f32_e32 v8, v8
	v_exp_f32_e32 v9, v6
	s_nop 0
	v_pk_add_f32 v[6:7], v[8:9], 1.0 op_sel_hi:[1,0]
	s_nop 0
	v_div_scale_f32 v8, s[4:5], v7, v7, v4
	v_rcp_f32_e32 v9, v8
	s_nop 0
	v_fma_f32 v19, -v8, v9, 1.0
	v_fmac_f32_e32 v9, v19, v9
	v_div_scale_f32 v19, vcc, v4, v7, v4
	v_mul_f32_e32 v20, v19, v9
	v_fma_f32 v21, -v8, v20, v19
	v_fmac_f32_e32 v20, v21, v9
	v_fma_f32 v8, -v8, v20, v19
	v_div_fmas_f32 v8, v8, v9, v20
	v_div_fixup_f32 v7, v8, v7, v4
	v_div_scale_f32 v4, s[4:5], v6, v6, v18
	v_rcp_f32_e32 v8, v4
	s_nop 0
	v_fma_f32 v9, -v4, v8, 1.0
	v_fmac_f32_e32 v8, v9, v8
	v_div_scale_f32 v9, vcc, v18, v6, v18
	v_mul_f32_e32 v19, v9, v8
	v_fma_f32 v20, -v4, v19, v9
	v_fmac_f32_e32 v19, v20, v8
	v_fma_f32 v4, -v4, v19, v9
	v_div_fmas_f32 v4, v4, v8, v19
	v_lshlrev_b32_e32 v8, 16, v5
	v_and_b32_e32 v9, 0xffff0000, v5
	v_div_fixup_f32 v6, v4, v6, v18
	v_mul_f32_e32 v4, 0xbfb8aa3b, v8
	v_mul_f32_e32 v5, 0xbfb8aa3b, v9
	v_exp_f32_e32 v4, v4
	v_exp_f32_e32 v5, v5
	v_pk_mul_f32 v[0:1], v[0:1], v[6:7]
	v_pk_add_f32 v[6:7], v[10:11], v[36:37] op_sel_hi:[1,0] neg_lo:[0,1] neg_hi:[0,1]
	v_cvt_pk_bf16_f32 v0, v0, v1
	v_pk_mul_f32 v[6:7], v[6:7], v[38:39] op_sel_hi:[1,0]
	v_pk_add_f32 v[4:5], v[4:5], 1.0 op_sel_hi:[1,0]
	v_pk_mul_f32 v[2:3], v[6:7], v[2:3]
	v_div_scale_f32 v6, s[4:5], v5, v5, v9
	v_rcp_f32_e32 v7, v6
	s_nop 0
	v_fma_f32 v10, -v6, v7, 1.0
	v_fmac_f32_e32 v7, v10, v7
	v_div_scale_f32 v10, vcc, v9, v5, v9
	v_mul_f32_e32 v11, v10, v7
	v_fma_f32 v18, -v6, v11, v10
	v_fmac_f32_e32 v11, v18, v7
	v_fma_f32 v6, -v6, v11, v10
	v_div_fmas_f32 v6, v6, v7, v11
	v_div_fixup_f32 v5, v6, v5, v9
	v_div_scale_f32 v6, s[4:5], v4, v4, v8
	v_rcp_f32_e32 v7, v6
	s_nop 0
	v_fma_f32 v9, -v6, v7, 1.0
	v_fmac_f32_e32 v7, v9, v7
	v_div_scale_f32 v9, vcc, v8, v4, v8
	v_mul_f32_e32 v10, v9, v7
	v_fma_f32 v11, -v6, v10, v9
	v_fmac_f32_e32 v10, v11, v7
	v_fma_f32 v6, -v6, v10, v9
	v_div_fmas_f32 v6, v6, v7, v10
	v_div_fixup_f32 v4, v6, v4, v8
	v_pk_mul_f32 v[2:3], v[2:3], v[4:5]
	v_pk_add_f32 v[6:7], v[12:13], v[36:37] op_sel_hi:[1,0] neg_lo:[0,1] neg_hi:[0,1]
	v_cvt_pk_bf16_f32 v1, v2, v3
	global_store_dwordx2 v[16:17], v[0:1], off offset:96
	s_waitcnt vmcnt(7)
	v_mov_b64_e32 v[4:5], v[168:169]
	v_mov_b64_e32 v[0:1], v[210:211]
	v_mov_b64_e32 v[2:3], v[212:213]
	v_pk_mul_f32 v[6:7], v[6:7], v[38:39] op_sel_hi:[1,0]
	v_lshlrev_b32_e32 v10, 16, v4
	v_and_b32_e32 v4, 0xffff0000, v4
	v_mul_f32_e32 v8, 0xbfb8aa3b, v10
	v_pk_mul_f32 v[0:1], v[6:7], v[0:1]
	v_mul_f32_e32 v6, 0xbfb8aa3b, v4
	v_exp_f32_e32 v8, v8
	v_exp_f32_e32 v9, v6
	s_nop 0
	v_pk_add_f32 v[6:7], v[8:9], 1.0 op_sel_hi:[1,0]
	s_nop 0
	v_div_scale_f32 v8, s[4:5], v7, v7, v4
	v_rcp_f32_e32 v9, v8
	s_nop 0
	v_fma_f32 v11, -v8, v9, 1.0
	v_fmac_f32_e32 v9, v11, v9
	v_div_scale_f32 v11, vcc, v4, v7, v4
	v_mul_f32_e32 v12, v11, v9
	v_fma_f32 v13, -v8, v12, v11
	v_fmac_f32_e32 v12, v13, v9
	v_fma_f32 v8, -v8, v12, v11
	v_div_fmas_f32 v8, v8, v9, v12
	v_div_fixup_f32 v7, v8, v7, v4
	v_div_scale_f32 v4, s[4:5], v6, v6, v10
	v_rcp_f32_e32 v8, v4
	s_nop 0
	v_fma_f32 v9, -v4, v8, 1.0
	v_fmac_f32_e32 v8, v9, v8
	v_div_scale_f32 v9, vcc, v10, v6, v10
	v_mul_f32_e32 v11, v9, v8
	v_fma_f32 v12, -v4, v11, v9
	v_fmac_f32_e32 v11, v12, v8
	v_fma_f32 v4, -v4, v11, v9
	v_div_fmas_f32 v4, v4, v8, v11
	v_lshlrev_b32_e32 v8, 16, v5
	v_and_b32_e32 v9, 0xffff0000, v5
	v_div_fixup_f32 v6, v4, v6, v10
	v_mul_f32_e32 v4, 0xbfb8aa3b, v8
	v_mul_f32_e32 v5, 0xbfb8aa3b, v9
	v_exp_f32_e32 v4, v4
	v_exp_f32_e32 v5, v5
	v_pk_mul_f32 v[0:1], v[0:1], v[6:7]
	v_pk_add_f32 v[6:7], v[14:15], v[36:37] op_sel_hi:[1,0] neg_lo:[0,1] neg_hi:[0,1]
	v_cvt_pk_bf16_f32 v0, v0, v1
	v_pk_mul_f32 v[6:7], v[6:7], v[38:39] op_sel_hi:[1,0]
	v_pk_add_f32 v[4:5], v[4:5], 1.0 op_sel_hi:[1,0]
	v_pk_mul_f32 v[2:3], v[6:7], v[2:3]
	v_div_scale_f32 v6, s[4:5], v5, v5, v9
	v_rcp_f32_e32 v7, v6
	s_nop 0
	v_fma_f32 v10, -v6, v7, 1.0
	v_fmac_f32_e32 v7, v10, v7
	v_div_scale_f32 v10, vcc, v9, v5, v9
	v_mul_f32_e32 v11, v10, v7
	v_fma_f32 v12, -v6, v11, v10
	v_fmac_f32_e32 v11, v12, v7
	v_fma_f32 v6, -v6, v11, v10
	v_div_fmas_f32 v6, v6, v7, v11
	v_div_fixup_f32 v5, v6, v5, v9
	v_div_scale_f32 v6, s[4:5], v4, v4, v8
	v_rcp_f32_e32 v7, v6
	s_nop 0
	v_fma_f32 v9, -v6, v7, 1.0
	v_fmac_f32_e32 v7, v9, v7
	v_div_scale_f32 v9, vcc, v8, v4, v8
	v_mul_f32_e32 v10, v9, v7
	v_fma_f32 v11, -v6, v10, v9
	v_fmac_f32_e32 v10, v11, v7
	v_fma_f32 v6, -v6, v10, v9
	v_div_fmas_f32 v6, v6, v7, v10
	v_div_fixup_f32 v4, v6, v4, v8
	v_pk_mul_f32 v[2:3], v[2:3], v[4:5]
	s_nop 0
	v_cvt_pk_bf16_f32 v1, v2, v3
	global_store_dwordx2 v[16:17], v[0:1], off offset:112
	s_setprio 0
	s_cbranch_scc1 .LBB0_872
.LBB0_877:
	s_cmp_lt_i32 s3, 4
	s_cbranch_scc0 .Lmy_m3_noprio
	s_setprio 1
